# grid barrier pollers watch the top arrival counter directly (no returned top atomic, no TOPGEN hop); P5 row-stat exchange acquire invalidate dropped (slots are sc1 stores and sc1 loads)
# baseline (speedup 1.0000x reference)
.Lgb1_lead:
	buffer_wbl2 sc1
	s_waitcnt vmcnt(0)
	v_mov_b32_e32 v1, 1
	global_atomic_add v0, v1, s[54:55] offset:1024

.Lgb1_spin:
	global_load_dword v1, v0, s[54:55] offset:1024 sc1
	s_waitcnt vmcnt(0)
	v_readfirstlane_b32 s0, v1
	s_cmp_ge_u32 s0, s9
	s_cbranch_scc1 .LBB0_92
	s_sleep 1
	s_add_u32 s1, s1, 1
	s_cmp_lt_u32 s1, 0x40000
	s_cbranch_scc1 .Lgb1_spin
	s_branch .LBB0_92

.LBB0_855:
	global_load_dword v79, v78, s[42:43] sc1
	s_mov_b64 s[50:51], -1
	s_waitcnt vmcnt(0)
	v_readfirstlane_b32 s9, v79
	s_cmp_gt_u32 s9, 31
	s_cbranch_scc1 .LBB0_854
	s_sleep 2
	global_load_dword v79, v78, s[42:43] sc1
	s_waitcnt vmcnt(0)
	v_readfirstlane_b32 s9, v79
	s_cmp_lt_u32 s9, 32
	s_cbranch_scc0 .LBB0_854
	s_sleep 2
	global_load_dword v79, v78, s[42:43] sc1
	s_waitcnt vmcnt(0)
	v_readfirstlane_b32 s9, v79
	s_cmp_lt_u32 s9, 32
	s_cbranch_scc0 .LBB0_854
	s_sleep 2
	global_load_dword v79, v78, s[42:43] sc1
	s_waitcnt vmcnt(0)
	v_readfirstlane_b32 s9, v79
	s_cmp_lt_u32 s9, 32
	s_cbranch_scc0 .LBB0_854
	s_sleep 2
	global_load_dword v79, v78, s[42:43] sc1
	s_waitcnt vmcnt(0)
	v_readfirstlane_b32 s9, v79
	s_cmp_lt_u32 s9, 32
	s_cbranch_scc0 .LBB0_854
	s_add_i32 s8, s8, -5
	s_cmp_eq_u32 s8, 0
	s_cselect_b64 s[50:51], -1, 0
	s_sleep 2
	s_branch .LBB0_854
.LBB0_861:
	s_waitcnt vmcnt(0)
.LBB0_862:
	v_lshl_add_u64 v[84:85], v[74:75], 1, s[28:29]
	v_lshlrev_b64 v[74:75], 1, v[198:199]
	v_cvt_pk_bf16_f32 v78, v124, v125
	v_cvt_pk_bf16_f32 v79, v126, v127
	v_lshl_add_u64 v[84:85], v[84:85], 0, v[74:75]
	global_store_dwordx2 v[84:85], v[78:79], off
	v_cvt_pk_bf16_f32 v78, v120, v121
	v_cvt_pk_bf16_f32 v79, v122, v123
	global_store_dwordx2 v[84:85], v[78:79], off offset:32
	v_cvt_pk_bf16_f32 v78, v116, v117
	v_cvt_pk_bf16_f32 v79, v118, v119
	global_store_dwordx2 v[84:85], v[78:79], off offset:256
	v_cvt_pk_bf16_f32 v78, v194, v195
	v_cvt_pk_bf16_f32 v79, v192, v193
	v_lshl_add_u64 v[14:15], v[14:15], 1, s[28:29]
	global_store_dwordx2 v[84:85], v[78:79], off offset:288
	v_cvt_pk_bf16_f32 v78, v188, v189
	v_cvt_pk_bf16_f32 v79, v114, v115
	v_lshl_add_u64 v[14:15], v[14:15], 0, v[74:75]
	global_store_dwordx2 v[14:15], v[78:79], off
	v_cvt_pk_bf16_f32 v78, v184, v185
	v_cvt_pk_bf16_f32 v79, v112, v113
	global_store_dwordx2 v[14:15], v[78:79], off offset:32
	v_cvt_pk_bf16_f32 v78, v180, v181
	v_cvt_pk_bf16_f32 v79, v182, v183
	global_store_dwordx2 v[14:15], v[78:79], off offset:256
	v_cvt_pk_bf16_f32 v78, v176, v177
	v_cvt_pk_bf16_f32 v79, v178, v179
	v_lshl_add_u64 v[12:13], v[12:13], 1, s[28:29]
	global_store_dwordx2 v[14:15], v[78:79], off offset:288
	v_cvt_pk_bf16_f32 v14, v172, v173
	v_cvt_pk_bf16_f32 v15, v174, v175
	v_lshl_add_u64 v[12:13], v[12:13], 0, v[74:75]
	global_store_dwordx2 v[12:13], v[14:15], off
	v_cvt_pk_bf16_f32 v14, v168, v169
	v_cvt_pk_bf16_f32 v15, v170, v171
	global_store_dwordx2 v[12:13], v[14:15], off offset:32
	v_cvt_pk_bf16_f32 v14, v164, v165
	v_cvt_pk_bf16_f32 v15, v166, v167
	global_store_dwordx2 v[12:13], v[14:15], off offset:256
	v_cvt_pk_bf16_f32 v14, v160, v161
	v_cvt_pk_bf16_f32 v15, v162, v163
	v_lshl_add_u64 v[8:9], v[8:9], 1, s[28:29]
	global_store_dwordx2 v[12:13], v[14:15], off offset:288
	v_cvt_pk_bf16_f32 v12, v156, v157
	v_cvt_pk_bf16_f32 v13, v158, v159
	v_lshl_add_u64 v[8:9], v[8:9], 0, v[74:75]
	global_store_dwordx2 v[8:9], v[12:13], off
	v_cvt_pk_bf16_f32 v12, v152, v153
	v_cvt_pk_bf16_f32 v13, v154, v155
	global_store_dwordx2 v[8:9], v[12:13], off offset:32
	v_cvt_pk_bf16_f32 v12, v148, v149
	v_cvt_pk_bf16_f32 v13, v150, v151
	global_store_dwordx2 v[8:9], v[12:13], off offset:256
	v_cvt_pk_bf16_f32 v12, v144, v145
	v_cvt_pk_bf16_f32 v13, v146, v147
	v_lshl_add_u64 v[10:11], v[10:11], 1, s[28:29]
	global_store_dwordx2 v[8:9], v[12:13], off offset:288
	v_cvt_pk_bf16_f32 v8, v60, v61
	v_cvt_pk_bf16_f32 v9, v62, v63
	v_lshl_add_u64 v[10:11], v[10:11], 0, v[74:75]
	global_store_dwordx2 v[10:11], v[8:9], off
	v_cvt_pk_bf16_f32 v8, v56, v57
	v_cvt_pk_bf16_f32 v9, v58, v59
	global_store_dwordx2 v[10:11], v[8:9], off offset:32
	v_cvt_pk_bf16_f32 v8, v52, v53
	v_cvt_pk_bf16_f32 v9, v54, v55
	global_store_dwordx2 v[10:11], v[8:9], off offset:256
	v_cvt_pk_bf16_f32 v8, v44, v45
	v_cvt_pk_bf16_f32 v9, v46, v47
	v_lshl_add_u64 v[6:7], v[6:7], 1, s[28:29]
	global_store_dwordx2 v[10:11], v[8:9], off offset:288
	v_cvt_pk_bf16_f32 v8, v48, v49
	v_cvt_pk_bf16_f32 v9, v50, v51
	v_lshl_add_u64 v[6:7], v[6:7], 0, v[74:75]
	global_store_dwordx2 v[6:7], v[8:9], off
	v_cvt_pk_bf16_f32 v8, v40, v41
	v_cvt_pk_bf16_f32 v9, v42, v43
	global_store_dwordx2 v[6:7], v[8:9], off offset:32
	v_cvt_pk_bf16_f32 v8, v32, v33
	v_cvt_pk_bf16_f32 v9, v34, v35
	global_store_dwordx2 v[6:7], v[8:9], off offset:256
	v_cvt_pk_bf16_f32 v8, v24, v25
	v_cvt_pk_bf16_f32 v9, v26, v27
	v_lshl_add_u64 v[2:3], v[2:3], 1, s[28:29]
	global_store_dwordx2 v[6:7], v[8:9], off offset:288
	v_cvt_pk_bf16_f32 v6, v36, v37
	v_cvt_pk_bf16_f32 v7, v38, v39
	v_lshl_add_u64 v[2:3], v[2:3], 0, v[74:75]
	global_store_dwordx2 v[2:3], v[6:7], off
	v_cvt_pk_bf16_f32 v6, v28, v29
	v_cvt_pk_bf16_f32 v7, v30, v31
	global_store_dwordx2 v[2:3], v[6:7], off offset:32
	v_cvt_pk_bf16_f32 v6, v16, v17
	v_cvt_pk_bf16_f32 v7, v18, v19
	global_store_dwordx2 v[2:3], v[6:7], off offset:256
	v_cvt_pk_bf16_f32 v6, v80, v81
	v_cvt_pk_bf16_f32 v7, v82, v83
	v_lshl_add_u64 v[4:5], v[4:5], 1, s[28:29]
	global_store_dwordx2 v[2:3], v[6:7], off offset:288
	v_cvt_pk_bf16_f32 v2, v76, v77
	v_cvt_pk_bf16_f32 v3, v22, v23
	v_lshl_add_u64 v[4:5], v[4:5], 0, v[74:75]
	global_store_dwordx2 v[4:5], v[2:3], off
	v_cvt_pk_bf16_f32 v2, v72, v73
	v_cvt_pk_bf16_f32 v3, v20, v21
	global_store_dwordx2 v[4:5], v[2:3], off offset:32
	v_cvt_pk_bf16_f32 v2, v68, v69
	v_cvt_pk_bf16_f32 v3, v70, v71
	global_store_dwordx2 v[4:5], v[2:3], off offset:256
	v_cvt_pk_bf16_f32 v2, v64, v65
	v_cvt_pk_bf16_f32 v3, v66, v67
	global_store_dwordx2 v[4:5], v[2:3], off offset:288
	s_waitcnt lgkmcnt(0)
	s_barrier
	s_and_saveexec_b64 s[42:43], s[4:5]
	s_cbranch_execz .LBB0_864
	s_ashr_i32 s39, s38, 31
	s_lshl_b64 s[4:5], s[38:39], 13
	s_add_u32 s0, s0, s4
	s_addc_u32 s1, s1, s5
	v_lshlrev_b64 v[2:3], 5, v[0:1]
	v_lshl_add_u64 v[2:3], s[0:1], 0, v[2:3]
	global_load_dword v1, v[2:3], off sc1
	global_load_dword v4, v[2:3], off offset:4 sc1
	global_load_dword v5, v[2:3], off offset:8 sc1
	global_load_dword v6, v[2:3], off offset:12 sc1
	global_load_dword v7, v[2:3], off offset:16 sc1
	global_load_dword v8, v[2:3], off offset:20 sc1
	global_load_dword v9, v[2:3], off offset:24 sc1
	s_nop 0
	global_load_dword v2, v[2:3], off offset:28 sc1
	v_mov_b32_e32 v3, 0x358637bd
	s_mov_b32 s0, 0xf800000
	v_lshl_add_u32 v0, v0, 2, 0
	s_waitcnt vmcnt(7)
	v_add_f32_e32 v1, 0, v1
	s_waitcnt vmcnt(6)
	v_add_f32_e32 v1, v1, v4
	s_waitcnt vmcnt(5)
	v_add_f32_e32 v1, v1, v5
	s_waitcnt vmcnt(4)
	v_add_f32_e32 v1, v1, v6
	s_waitcnt vmcnt(3)
	v_add_f32_e32 v1, v1, v7
	s_waitcnt vmcnt(2)
	v_add_f32_e32 v1, v1, v8
	s_waitcnt vmcnt(1)
	v_add_f32_e32 v1, v1, v9
	s_waitcnt vmcnt(0)
	v_add_f32_e32 v1, v1, v2
	v_fmac_f32_e32 v3, 0x3a000000, v1
	v_mul_f32_e32 v1, 0x4f800000, v3
	v_cmp_gt_f32_e32 vcc, s0, v3
	s_nop 1
	v_cndmask_b32_e32 v1, v3, v1, vcc
	v_sqrt_f32_e32 v2, v1
	v_mov_b32_e32 v3, 0x260
	v_add_u32_e32 v4, -1, v2
	v_add_u32_e32 v5, 1, v2
	v_fma_f32 v6, -v4, v2, v1
	v_fma_f32 v7, -v5, v2, v1
	v_cmp_ge_f32_e64 s[4:5], 0, v6
	s_nop 1
	v_cndmask_b32_e64 v2, v2, v4, s[4:5]
	v_cmp_lt_f32_e64 s[4:5], 0, v7
	s_nop 1
	v_cndmask_b32_e64 v2, v2, v5, s[4:5]
	v_mul_f32_e32 v4, 0x37800000, v2
	v_cndmask_b32_e32 v2, v2, v4, vcc
	v_cmp_class_f32_e32 vcc, v1, v3
	s_nop 1
	v_cndmask_b32_e32 v1, v2, v1, vcc
	v_div_scale_f32 v2, s[0:1], v1, v1, 1.0
	v_rcp_f32_e32 v3, v2
	v_div_scale_f32 v4, vcc, 1.0, v1, 1.0
	v_fma_f32 v5, -v2, v3, 1.0
	v_fmac_f32_e32 v3, v5, v3
	v_mul_f32_e32 v5, v4, v3
	v_fma_f32 v6, -v2, v5, v4
	v_fmac_f32_e32 v5, v6, v3
	v_fma_f32 v2, -v2, v5, v4
	v_div_fmas_f32 v2, v2, v3, v5
	v_div_fixup_f32 v1, v2, v1, 1.0
	ds_write_b32 v0, v1 offset:4096
